# P3 branch-projection GEMM: skip the 16 MFMAs per phase that multiply the zero-padded half of the pair's weight tile
# speedup vs baseline: 1.0283x; 1.0080x over previous
.LBB0_590:
	s_add_i32 s35, s6, 2
	s_add_u32 s7, s4, 0xfffc0080
	s_addc_u32 s44, s5, -1
	s_add_i32 s45, 0, 0x10000
	s_cmp_eq_u32 s80, s6
	s_cselect_b32 s49, s26, s44
	s_cselect_b32 s48, s27, s7
	s_cselect_b32 s7, s28, s34
	s_cselect_b32 s6, s29, s31
	s_add_i32 s52, 0, 0x14000
	v_add_u32_e32 v152, s45, v157
	v_add_u32_e32 v174, s52, v157
	ds_read_b128 v[130:133], v152
	ds_read_b128 v[134:137], v152 offset:1024
	ds_read_b128 v[138:141], v152 offset:2048
	ds_read_b128 v[152:155], v152 offset:3072
	ds_read_b128 v[162:165], v174
	ds_read_b128 v[166:169], v174 offset:1024
	ds_read_b128 v[170:173], v174 offset:2048
	ds_read_b128 v[174:177], v174 offset:3072
	v_lshl_add_u64 v[214:215], s[4:5], 0, v[148:149]
	s_add_i32 m0, s57, 0xc000
	ds_read_b128 v[178:181], v161
	ds_read_b128 v[182:185], v161 offset:1024
	ds_read_b128 v[186:189], v161 offset:2048
	ds_read_b128 v[190:193], v161 offset:3072
	ds_read_b128 v[194:197], v161 offset:4096
	ds_read_b128 v[198:201], v161 offset:5120
	ds_read_b128 v[202:205], v161 offset:6144
	ds_read_b128 v[206:209], v161 offset:7168
	global_load_lds_dwordx4 v[214:215], off
	v_lshl_add_u64 v[214:215], s[4:5], 0, v[150:151]
	s_add_i32 m0, s57, 0xe000
	s_nop 0
	global_load_lds_dwordx4 v[214:215], off
	s_waitcnt vmcnt(8)
	s_waitcnt lgkmcnt(0)
	s_barrier
	s_setprio 1
	s_waitcnt lgkmcnt(0)
	s_cmp_lt_i32 s35, 6
	s_cbranch_scc0 .Lp3_hi1
	v_mfma_f32_16x16x32_bf16 v[122:125], v[130:133], v[178:181], v[122:125]
	v_mfma_f32_16x16x32_bf16 v[114:117], v[138:141], v[178:181], v[114:117]
	v_mfma_f32_16x16x32_bf16 v[106:109], v[130:133], v[186:189], v[106:109]
	v_mfma_f32_16x16x32_bf16 v[98:101], v[138:141], v[186:189], v[98:101]
	v_mfma_f32_16x16x32_bf16 v[90:93], v[130:133], v[194:197], v[90:93]
	v_mfma_f32_16x16x32_bf16 v[82:85], v[138:141], v[194:197], v[82:85]
	v_mfma_f32_16x16x32_bf16 v[74:77], v[130:133], v[202:205], v[74:77]
	v_mfma_f32_16x16x32_bf16 v[66:69], v[138:141], v[202:205], v[66:69]
	v_mfma_f32_16x16x32_bf16 v[122:125], v[134:137], v[182:185], v[122:125]
	v_mfma_f32_16x16x32_bf16 v[114:117], v[152:155], v[182:185], v[114:117]
	v_mfma_f32_16x16x32_bf16 v[106:109], v[134:137], v[190:193], v[106:109]
	v_mfma_f32_16x16x32_bf16 v[98:101], v[152:155], v[190:193], v[98:101]
	v_mfma_f32_16x16x32_bf16 v[90:93], v[134:137], v[198:201], v[90:93]
	v_mfma_f32_16x16x32_bf16 v[82:85], v[152:155], v[198:201], v[82:85]
	v_mfma_f32_16x16x32_bf16 v[74:77], v[134:137], v[206:209], v[74:77]
	v_mfma_f32_16x16x32_bf16 v[66:69], v[152:155], v[206:209], v[66:69]
	s_branch .Lp3_end1
.Lp3_hi1:
	v_mfma_f32_16x16x32_bf16 v[126:129], v[162:165], v[178:181], v[126:129]
	v_mfma_f32_16x16x32_bf16 v[118:121], v[170:173], v[178:181], v[118:121]
	v_mfma_f32_16x16x32_bf16 v[110:113], v[162:165], v[186:189], v[110:113]
	v_mfma_f32_16x16x32_bf16 v[102:105], v[170:173], v[186:189], v[102:105]
	v_mfma_f32_16x16x32_bf16 v[94:97], v[162:165], v[194:197], v[94:97]
	v_mfma_f32_16x16x32_bf16 v[86:89], v[170:173], v[194:197], v[86:89]
	v_mfma_f32_16x16x32_bf16 v[78:81], v[162:165], v[202:205], v[78:81]
	v_mfma_f32_16x16x32_bf16 v[70:73], v[170:173], v[202:205], v[70:73]
	v_mfma_f32_16x16x32_bf16 v[126:129], v[166:169], v[182:185], v[126:129]
	v_mfma_f32_16x16x32_bf16 v[118:121], v[174:177], v[182:185], v[118:121]
	v_mfma_f32_16x16x32_bf16 v[110:113], v[166:169], v[190:193], v[110:113]
	v_mfma_f32_16x16x32_bf16 v[102:105], v[174:177], v[190:193], v[102:105]
	v_mfma_f32_16x16x32_bf16 v[94:97], v[166:169], v[198:201], v[94:97]
	v_mfma_f32_16x16x32_bf16 v[86:89], v[174:177], v[198:201], v[86:89]
	v_mfma_f32_16x16x32_bf16 v[78:81], v[166:169], v[206:209], v[78:81]
	v_mfma_f32_16x16x32_bf16 v[70:73], v[174:177], v[206:209], v[70:73]
.Lp3_end1:
	s_setprio 0
	s_barrier
	s_add_i32 s44, s45, s56
	v_lshl_add_u64 v[214:215], s[6:7], 0, v[0:1]
	s_mov_b32 m0, s44
	ds_read_b128 v[178:181], v161 offset:16384
	ds_read_b128 v[182:185], v161 offset:17408
	ds_read_b128 v[186:189], v161 offset:18432
	ds_read_b128 v[190:193], v161 offset:19456
	ds_read_b128 v[194:197], v161 offset:20480
	ds_read_b128 v[198:201], v161 offset:21504
	ds_read_b128 v[202:205], v161 offset:22528
	ds_read_b128 v[206:209], v161 offset:23552
	global_load_lds_dwordx4 v[214:215], off
	s_add_i32 m0, s44, 0x2000
	s_add_u32 s44, s6, 0x20000
	v_lshl_add_u64 v[216:217], s[6:7], 0, v[142:143]
	s_addc_u32 s45, s7, 0
	s_add_i32 s52, s52, s56
	global_load_lds_dwordx4 v[216:217], off
	v_lshl_add_u64 v[218:219], s[44:45], 0, v[0:1]
	s_mov_b32 m0, s52
	v_lshl_add_u64 v[220:221], s[48:49], 0, v[144:145]
	global_load_lds_dwordx4 v[218:219], off
	v_lshl_add_u64 v[218:219], s[44:45], 0, v[142:143]
	s_add_i32 m0, s52, 0x2000
	s_nop 0
	global_load_lds_dwordx4 v[218:219], off
	v_lshl_add_u64 v[218:219], s[48:49], 0, v[146:147]
	s_mov_b32 m0, s57
	s_nop 0
	global_load_lds_dwordx4 v[218:219], off
	s_mov_b32 m0, s64
	s_nop 0
	global_load_lds_dwordx4 v[220:221], off
	s_waitcnt vmcnt(8)
	s_waitcnt lgkmcnt(0)
	s_barrier
	s_setprio 1
	s_waitcnt lgkmcnt(0)
	s_cmp_lt_i32 s35, 6
	s_cbranch_scc0 .Lp3_hi2
	v_mfma_f32_16x16x32_bf16 v[58:61], v[130:133], v[178:181], v[58:61]
	v_mfma_f32_16x16x32_bf16 v[50:53], v[138:141], v[178:181], v[50:53]
	v_mfma_f32_16x16x32_bf16 v[42:45], v[130:133], v[186:189], v[42:45]
	v_mfma_f32_16x16x32_bf16 v[34:37], v[138:141], v[186:189], v[34:37]
	v_mfma_f32_16x16x32_bf16 v[26:29], v[130:133], v[194:197], v[26:29]
	v_mfma_f32_16x16x32_bf16 v[18:21], v[138:141], v[194:197], v[18:21]
	v_mfma_f32_16x16x32_bf16 v[10:13], v[130:133], v[202:205], v[10:13]
	v_mfma_f32_16x16x32_bf16 v[6:9], v[138:141], v[202:205], v[6:9]
	v_mfma_f32_16x16x32_bf16 v[58:61], v[134:137], v[182:185], v[58:61]
	v_mfma_f32_16x16x32_bf16 v[50:53], v[152:155], v[182:185], v[50:53]
	v_mfma_f32_16x16x32_bf16 v[42:45], v[134:137], v[190:193], v[42:45]
	v_mfma_f32_16x16x32_bf16 v[34:37], v[152:155], v[190:193], v[34:37]
	v_mfma_f32_16x16x32_bf16 v[26:29], v[134:137], v[198:201], v[26:29]
	v_mfma_f32_16x16x32_bf16 v[18:21], v[152:155], v[198:201], v[18:21]
	v_mfma_f32_16x16x32_bf16 v[10:13], v[134:137], v[206:209], v[10:13]
	v_mfma_f32_16x16x32_bf16 v[6:9], v[152:155], v[206:209], v[6:9]
	s_branch .Lp3_end2
.Lp3_hi2:
	v_mfma_f32_16x16x32_bf16 v[62:65], v[162:165], v[178:181], v[62:65]
	v_mfma_f32_16x16x32_bf16 v[54:57], v[170:173], v[178:181], v[54:57]
	v_mfma_f32_16x16x32_bf16 v[46:49], v[162:165], v[186:189], v[46:49]
	v_mfma_f32_16x16x32_bf16 v[38:41], v[170:173], v[186:189], v[38:41]
	v_mfma_f32_16x16x32_bf16 v[30:33], v[162:165], v[194:197], v[30:33]
	v_mfma_f32_16x16x32_bf16 v[22:25], v[170:173], v[194:197], v[22:25]
	v_mfma_f32_16x16x32_bf16 v[14:17], v[162:165], v[202:205], v[14:17]
	v_mfma_f32_16x16x32_bf16 v[2:5], v[170:173], v[202:205], v[2:5]
	v_mfma_f32_16x16x32_bf16 v[62:65], v[166:169], v[182:185], v[62:65]
	v_mfma_f32_16x16x32_bf16 v[54:57], v[174:177], v[182:185], v[54:57]
	v_mfma_f32_16x16x32_bf16 v[46:49], v[166:169], v[190:193], v[46:49]
	v_mfma_f32_16x16x32_bf16 v[38:41], v[174:177], v[190:193], v[38:41]
	v_mfma_f32_16x16x32_bf16 v[30:33], v[166:169], v[198:201], v[30:33]
	v_mfma_f32_16x16x32_bf16 v[22:25], v[174:177], v[198:201], v[22:25]
	v_mfma_f32_16x16x32_bf16 v[14:17], v[166:169], v[206:209], v[14:17]
	v_mfma_f32_16x16x32_bf16 v[2:5], v[174:177], v[206:209], v[2:5]
.Lp3_end2:
	s_setprio 0
	s_barrier
	s_add_i32 s52, 0, 0x18000
	s_add_i32 s53, 0, 0x1c000
	v_add_u32_e32 v152, s52, v157
	v_add_u32_e32 v174, s53, v157
	ds_read_b128 v[130:133], v152
	ds_read_b128 v[134:137], v152 offset:1024
	ds_read_b128 v[138:141], v152 offset:2048
	ds_read_b128 v[152:155], v152 offset:3072
	ds_read_b128 v[162:165], v174
	ds_read_b128 v[166:169], v174 offset:1024
	ds_read_b128 v[170:173], v174 offset:2048
	ds_read_b128 v[174:177], v174 offset:3072
	s_add_u32 s44, s48, 0x40000
	s_addc_u32 s45, s49, 0
	s_mov_b32 m0, s65
	v_lshl_add_u64 v[222:223], s[44:45], 0, v[146:147]
	ds_read_b128 v[178:181], v161 offset:32768
	ds_read_b128 v[182:185], v161 offset:33792
	ds_read_b128 v[186:189], v161 offset:34816
	ds_read_b128 v[190:193], v161 offset:35840
	ds_read_b128 v[194:197], v161 offset:36864
	ds_read_b128 v[198:201], v161 offset:37888
	ds_read_b128 v[202:205], v161 offset:38912
	ds_read_b128 v[206:209], v161 offset:39936
	global_load_lds_dwordx4 v[222:223], off
	v_lshl_add_u64 v[222:223], s[44:45], 0, v[144:145]
	s_mov_b32 m0, s66
	s_nop 0
	global_load_lds_dwordx4 v[222:223], off
	s_waitcnt vmcnt(8)
	s_waitcnt lgkmcnt(0)
	s_barrier
	s_setprio 1
	s_waitcnt lgkmcnt(0)
	s_cmp_lt_i32 s35, 6
	s_cbranch_scc0 .Lp3_hi3
	v_mfma_f32_16x16x32_bf16 v[122:125], v[130:133], v[178:181], v[122:125]
	v_mfma_f32_16x16x32_bf16 v[114:117], v[138:141], v[178:181], v[114:117]
	v_mfma_f32_16x16x32_bf16 v[106:109], v[130:133], v[186:189], v[106:109]
	v_mfma_f32_16x16x32_bf16 v[98:101], v[138:141], v[186:189], v[98:101]
	v_mfma_f32_16x16x32_bf16 v[90:93], v[130:133], v[194:197], v[90:93]
	v_mfma_f32_16x16x32_bf16 v[82:85], v[138:141], v[194:197], v[82:85]
	v_mfma_f32_16x16x32_bf16 v[74:77], v[130:133], v[202:205], v[74:77]
	v_mfma_f32_16x16x32_bf16 v[66:69], v[138:141], v[202:205], v[66:69]
	v_mfma_f32_16x16x32_bf16 v[122:125], v[134:137], v[182:185], v[122:125]
	v_mfma_f32_16x16x32_bf16 v[114:117], v[152:155], v[182:185], v[114:117]
	v_mfma_f32_16x16x32_bf16 v[106:109], v[134:137], v[190:193], v[106:109]
	v_mfma_f32_16x16x32_bf16 v[98:101], v[152:155], v[190:193], v[98:101]
	v_mfma_f32_16x16x32_bf16 v[90:93], v[134:137], v[198:201], v[90:93]
	v_mfma_f32_16x16x32_bf16 v[82:85], v[152:155], v[198:201], v[82:85]
	v_mfma_f32_16x16x32_bf16 v[74:77], v[134:137], v[206:209], v[74:77]
	v_mfma_f32_16x16x32_bf16 v[66:69], v[152:155], v[206:209], v[66:69]
	s_branch .Lp3_end3

.Lp3_end3:
	s_setprio 0
	s_barrier
	s_add_i32 s44, s52, s56
	v_lshl_add_u64 v[214:215], v[214:215], 0, s[78:79]
	s_mov_b32 m0, s44
	ds_read_b128 v[178:181], v161 offset:49152
	ds_read_b128 v[182:185], v161 offset:50176
	ds_read_b128 v[186:189], v161 offset:51200
	ds_read_b128 v[190:193], v161 offset:52224
	ds_read_b128 v[194:197], v161 offset:53248
	ds_read_b128 v[198:201], v161 offset:54272
	ds_read_b128 v[202:205], v161 offset:55296
	ds_read_b128 v[206:209], v161 offset:56320
	global_load_lds_dwordx4 v[214:215], off
	s_add_i32 m0, s44, 0x2000
	s_add_u32 s6, s6, 0x20080
	v_lshl_add_u64 v[214:215], v[216:217], 0, s[78:79]
	s_addc_u32 s7, s7, 0
	s_add_i32 s44, s53, s56
	global_load_lds_dwordx4 v[214:215], off
	v_lshl_add_u64 v[214:215], s[6:7], 0, v[0:1]
	s_mov_b32 m0, s44
	s_nop 0
	global_load_lds_dwordx4 v[214:215], off
	v_lshl_add_u64 v[214:215], s[6:7], 0, v[142:143]
	s_add_i32 m0, s44, 0x2000
	s_nop 0
	global_load_lds_dwordx4 v[214:215], off
	v_lshl_add_u64 v[214:215], v[218:219], 0, s[78:79]
	s_mov_b32 m0, s73
	s_nop 0
	global_load_lds_dwordx4 v[214:215], off
	v_lshl_add_u64 v[214:215], v[220:221], 0, s[78:79]
	s_mov_b32 m0, s76
	s_nop 0
	global_load_lds_dwordx4 v[214:215], off
	s_waitcnt vmcnt(8)
	s_waitcnt lgkmcnt(0)
	s_barrier
	s_setprio 1
	s_waitcnt lgkmcnt(0)
	s_cmp_lt_i32 s35, 6
	s_cbranch_scc0 .Lp3_hi4
	v_mfma_f32_16x16x32_bf16 v[58:61], v[130:133], v[178:181], v[58:61]
	v_mfma_f32_16x16x32_bf16 v[50:53], v[138:141], v[178:181], v[50:53]
	v_mfma_f32_16x16x32_bf16 v[42:45], v[130:133], v[186:189], v[42:45]
	v_mfma_f32_16x16x32_bf16 v[34:37], v[138:141], v[186:189], v[34:37]
	v_mfma_f32_16x16x32_bf16 v[26:29], v[130:133], v[194:197], v[26:29]
	v_mfma_f32_16x16x32_bf16 v[18:21], v[138:141], v[194:197], v[18:21]
	v_mfma_f32_16x16x32_bf16 v[10:13], v[130:133], v[202:205], v[10:13]
	v_mfma_f32_16x16x32_bf16 v[6:9], v[138:141], v[202:205], v[6:9]
	v_mfma_f32_16x16x32_bf16 v[58:61], v[134:137], v[182:185], v[58:61]
	v_mfma_f32_16x16x32_bf16 v[50:53], v[152:155], v[182:185], v[50:53]
	v_mfma_f32_16x16x32_bf16 v[42:45], v[134:137], v[190:193], v[42:45]
	v_mfma_f32_16x16x32_bf16 v[34:37], v[152:155], v[190:193], v[34:37]
	v_mfma_f32_16x16x32_bf16 v[26:29], v[134:137], v[198:201], v[26:29]
	v_mfma_f32_16x16x32_bf16 v[18:21], v[152:155], v[198:201], v[18:21]
	v_mfma_f32_16x16x32_bf16 v[10:13], v[134:137], v[206:209], v[10:13]
	v_mfma_f32_16x16x32_bf16 v[6:9], v[152:155], v[206:209], v[6:9]
	s_branch .Lp3_end4

.Lp3_end4:
	s_setprio 0
	s_barrier
	s_add_u32 s4, s4, 0x100
	s_addc_u32 s5, s5, 0
	s_add_u32 s31, s31, 0x100
	s_addc_u32 s34, s34, 0
	s_cmp_ge_i32 s35, s43
	s_mov_b32 s6, s35
	s_cbranch_scc0 .LBB0_590
	s_and_b64 vcc, exec, s[14:15]
	s_cbranch_vccz .LBB0_593
